# hand-written EpiGab epilogues (P6 merge-gate GEMMs): all rstd/bias loads up front, packed f32 sigmoid
# speedup vs baseline: 1.0639x; 1.0032x over previous
.LBB0_1058:
	v_lshl_add_u32 v202, s61, 8, v166
	v_lshl_add_u32 v203, s30, 8, v164
	v_lshlrev_b32_e32 v204, 12, v203
	v_lshl_add_u32 v204, v202, 1, v204
	v_lshlrev_b32_e32 v202, 2, v202
	v_lshlrev_b32_e32 v203, 2, v203
	global_load_dwordx4 v[170:173], v202, s[16:17]
	global_load_dwordx4 v[174:177], v202, s[16:17] offset:16
	global_load_dwordx4 v[178:181], v202, s[16:17] offset:512
	global_load_dwordx4 v[182:185], v202, s[16:17] offset:528
	global_load_dword v186, v203, s[24:25]
	global_load_dword v188, v203, s[24:25] offset:64
	global_load_dword v190, v203, s[24:25] offset:128
	global_load_dword v192, v203, s[24:25] offset:192
	global_load_dword v194, v203, s[24:25] offset:512
	global_load_dword v196, v203, s[24:25] offset:576
	global_load_dword v198, v203, s[24:25] offset:640
	global_load_dword v200, v203, s[24:25] offset:704
	v_mov_b32_e32 v214, 0xbfb8aa3b
	v_mov_b32_e32 v215, 0xbfb8aa3b
	v_mov_b32_e32 v216, 1.0
	v_mov_b32_e32 v217, 1.0
	v_mov_b32_e32 v206, v204
	v_add_u32_e32 v207, 0x10000, v204
	v_add_u32_e32 v208, 0x20000, v204
	v_add_u32_e32 v209, 0x30000, v204
	v_add_u32_e32 v210, 0x80000, v204
	v_add_u32_e32 v211, 0x90000, v204
	v_add_u32_e32 v212, 0xa0000, v204
	v_add_u32_e32 v213, 0xb0000, v204
	s_waitcnt vmcnt(0)
	v_pk_mul_f32 v[170:171], v[170:171], v[214:215]
	v_pk_mul_f32 v[172:173], v[172:173], v[214:215]
	v_pk_mul_f32 v[174:175], v[174:175], v[214:215]
	v_pk_mul_f32 v[176:177], v[176:177], v[214:215]
	v_pk_mul_f32 v[178:179], v[178:179], v[214:215]
	v_pk_mul_f32 v[180:181], v[180:181], v[214:215]
	v_pk_mul_f32 v[182:183], v[182:183], v[214:215]
	v_pk_mul_f32 v[184:185], v[184:185], v[214:215]
	v_mul_f32_e32 v186, 0xbfb8aa3b, v186
	v_mul_f32_e32 v188, 0xbfb8aa3b, v188
	v_mul_f32_e32 v190, 0xbfb8aa3b, v190
	v_mul_f32_e32 v192, 0xbfb8aa3b, v192
	v_mul_f32_e32 v194, 0xbfb8aa3b, v194
	v_mul_f32_e32 v196, 0xbfb8aa3b, v196
	v_mul_f32_e32 v198, 0xbfb8aa3b, v198
	v_mul_f32_e32 v200, 0xbfb8aa3b, v200
	v_pk_fma_f32 v[140:141], v[140:141], v[186:187], v[170:171] op_sel_hi:[1,0,1]
	v_pk_fma_f32 v[142:143], v[142:143], v[186:187], v[172:173] op_sel_hi:[1,0,1]
	v_pk_fma_f32 v[136:137], v[136:137], v[186:187], v[174:175] op_sel_hi:[1,0,1]
	v_pk_fma_f32 v[138:139], v[138:139], v[186:187], v[176:177] op_sel_hi:[1,0,1]
	v_pk_fma_f32 v[132:133], v[132:133], v[186:187], v[178:179] op_sel_hi:[1,0,1]
	v_pk_fma_f32 v[134:135], v[134:135], v[186:187], v[180:181] op_sel_hi:[1,0,1]
	v_pk_fma_f32 v[128:129], v[128:129], v[186:187], v[182:183] op_sel_hi:[1,0,1]
	v_pk_fma_f32 v[130:131], v[130:131], v[186:187], v[184:185] op_sel_hi:[1,0,1]
	v_exp_f32_e32 v140, v140
	v_exp_f32_e32 v141, v141
	v_exp_f32_e32 v142, v142
	v_exp_f32_e32 v143, v143
	v_exp_f32_e32 v136, v136
	v_exp_f32_e32 v137, v137
	v_exp_f32_e32 v138, v138
	v_exp_f32_e32 v139, v139
	v_exp_f32_e32 v132, v132
	v_exp_f32_e32 v133, v133
	v_exp_f32_e32 v134, v134
	v_exp_f32_e32 v135, v135
	v_exp_f32_e32 v128, v128
	v_exp_f32_e32 v129, v129
	v_exp_f32_e32 v130, v130
	v_exp_f32_e32 v131, v131
	s_nop 0
	v_pk_add_f32 v[140:141], v[140:141], v[216:217]
	v_pk_add_f32 v[142:143], v[142:143], v[216:217]
	v_pk_add_f32 v[136:137], v[136:137], v[216:217]
	v_pk_add_f32 v[138:139], v[138:139], v[216:217]
	v_pk_add_f32 v[132:133], v[132:133], v[216:217]
	v_pk_add_f32 v[134:135], v[134:135], v[216:217]
	v_pk_add_f32 v[128:129], v[128:129], v[216:217]
	v_pk_add_f32 v[130:131], v[130:131], v[216:217]
	v_rcp_f32_e32 v140, v140
	v_rcp_f32_e32 v141, v141
	v_rcp_f32_e32 v142, v142
	v_rcp_f32_e32 v143, v143
	v_rcp_f32_e32 v136, v136
	v_rcp_f32_e32 v137, v137
	v_rcp_f32_e32 v138, v138
	v_rcp_f32_e32 v139, v139
	v_rcp_f32_e32 v132, v132
	v_rcp_f32_e32 v133, v133
	v_rcp_f32_e32 v134, v134
	v_rcp_f32_e32 v135, v135
	v_rcp_f32_e32 v128, v128
	v_rcp_f32_e32 v129, v129
	v_rcp_f32_e32 v130, v130
	v_rcp_f32_e32 v131, v131
	s_nop 0
	v_cvt_pk_bf16_f32 v140, v140, v141
	v_cvt_pk_bf16_f32 v141, v142, v143
	v_cvt_pk_bf16_f32 v142, v136, v137
	v_cvt_pk_bf16_f32 v143, v138, v139
	global_store_dwordx4 v206, v[140:143], s[10:11]
	v_cvt_pk_bf16_f32 v132, v132, v133
	v_cvt_pk_bf16_f32 v133, v134, v135
	v_cvt_pk_bf16_f32 v134, v128, v129
	v_cvt_pk_bf16_f32 v135, v130, v131
	global_store_dwordx4 v206, v[132:135], s[10:11] offset:256
	v_pk_fma_f32 v[124:125], v[124:125], v[188:189], v[170:171] op_sel_hi:[1,0,1]
	v_pk_fma_f32 v[126:127], v[126:127], v[188:189], v[172:173] op_sel_hi:[1,0,1]
	v_pk_fma_f32 v[120:121], v[120:121], v[188:189], v[174:175] op_sel_hi:[1,0,1]
	v_pk_fma_f32 v[122:123], v[122:123], v[188:189], v[176:177] op_sel_hi:[1,0,1]
	v_pk_fma_f32 v[116:117], v[116:117], v[188:189], v[178:179] op_sel_hi:[1,0,1]
	v_pk_fma_f32 v[118:119], v[118:119], v[188:189], v[180:181] op_sel_hi:[1,0,1]
	v_pk_fma_f32 v[112:113], v[112:113], v[188:189], v[182:183] op_sel_hi:[1,0,1]
	v_pk_fma_f32 v[114:115], v[114:115], v[188:189], v[184:185] op_sel_hi:[1,0,1]
	v_exp_f32_e32 v124, v124
	v_exp_f32_e32 v125, v125
	v_exp_f32_e32 v126, v126
	v_exp_f32_e32 v127, v127
	v_exp_f32_e32 v120, v120
	v_exp_f32_e32 v121, v121
	v_exp_f32_e32 v122, v122
	v_exp_f32_e32 v123, v123
	v_exp_f32_e32 v116, v116
	v_exp_f32_e32 v117, v117
	v_exp_f32_e32 v118, v118
	v_exp_f32_e32 v119, v119
	v_exp_f32_e32 v112, v112
	v_exp_f32_e32 v113, v113
	v_exp_f32_e32 v114, v114
	v_exp_f32_e32 v115, v115
	s_nop 0
	v_pk_add_f32 v[124:125], v[124:125], v[216:217]
	v_pk_add_f32 v[126:127], v[126:127], v[216:217]
	v_pk_add_f32 v[120:121], v[120:121], v[216:217]
	v_pk_add_f32 v[122:123], v[122:123], v[216:217]
	v_pk_add_f32 v[116:117], v[116:117], v[216:217]
	v_pk_add_f32 v[118:119], v[118:119], v[216:217]
	v_pk_add_f32 v[112:113], v[112:113], v[216:217]
	v_pk_add_f32 v[114:115], v[114:115], v[216:217]
	v_rcp_f32_e32 v124, v124
	v_rcp_f32_e32 v125, v125
	v_rcp_f32_e32 v126, v126
	v_rcp_f32_e32 v127, v127
	v_rcp_f32_e32 v120, v120
	v_rcp_f32_e32 v121, v121
	v_rcp_f32_e32 v122, v122
	v_rcp_f32_e32 v123, v123
	v_rcp_f32_e32 v116, v116
	v_rcp_f32_e32 v117, v117
	v_rcp_f32_e32 v118, v118
	v_rcp_f32_e32 v119, v119
	v_rcp_f32_e32 v112, v112
	v_rcp_f32_e32 v113, v113
	v_rcp_f32_e32 v114, v114
	v_rcp_f32_e32 v115, v115
	s_nop 0
	v_cvt_pk_bf16_f32 v124, v124, v125
	v_cvt_pk_bf16_f32 v125, v126, v127
	v_cvt_pk_bf16_f32 v126, v120, v121
	v_cvt_pk_bf16_f32 v127, v122, v123
	global_store_dwordx4 v207, v[124:127], s[10:11]
	v_cvt_pk_bf16_f32 v116, v116, v117
	v_cvt_pk_bf16_f32 v117, v118, v119
	v_cvt_pk_bf16_f32 v118, v112, v113
	v_cvt_pk_bf16_f32 v119, v114, v115
	global_store_dwordx4 v207, v[116:119], s[10:11] offset:256
	v_pk_fma_f32 v[108:109], v[108:109], v[190:191], v[170:171] op_sel_hi:[1,0,1]
	v_pk_fma_f32 v[110:111], v[110:111], v[190:191], v[172:173] op_sel_hi:[1,0,1]
	v_pk_fma_f32 v[104:105], v[104:105], v[190:191], v[174:175] op_sel_hi:[1,0,1]
	v_pk_fma_f32 v[106:107], v[106:107], v[190:191], v[176:177] op_sel_hi:[1,0,1]
	v_pk_fma_f32 v[100:101], v[100:101], v[190:191], v[178:179] op_sel_hi:[1,0,1]
	v_pk_fma_f32 v[102:103], v[102:103], v[190:191], v[180:181] op_sel_hi:[1,0,1]
	v_pk_fma_f32 v[96:97], v[96:97], v[190:191], v[182:183] op_sel_hi:[1,0,1]
	v_pk_fma_f32 v[98:99], v[98:99], v[190:191], v[184:185] op_sel_hi:[1,0,1]
	v_exp_f32_e32 v108, v108
	v_exp_f32_e32 v109, v109
	v_exp_f32_e32 v110, v110
	v_exp_f32_e32 v111, v111
	v_exp_f32_e32 v104, v104
	v_exp_f32_e32 v105, v105
	v_exp_f32_e32 v106, v106
	v_exp_f32_e32 v107, v107
	v_exp_f32_e32 v100, v100
	v_exp_f32_e32 v101, v101
	v_exp_f32_e32 v102, v102
	v_exp_f32_e32 v103, v103
	v_exp_f32_e32 v96, v96
	v_exp_f32_e32 v97, v97
	v_exp_f32_e32 v98, v98
	v_exp_f32_e32 v99, v99
	s_nop 0
	v_pk_add_f32 v[108:109], v[108:109], v[216:217]
	v_pk_add_f32 v[110:111], v[110:111], v[216:217]
	v_pk_add_f32 v[104:105], v[104:105], v[216:217]
	v_pk_add_f32 v[106:107], v[106:107], v[216:217]
	v_pk_add_f32 v[100:101], v[100:101], v[216:217]
	v_pk_add_f32 v[102:103], v[102:103], v[216:217]
	v_pk_add_f32 v[96:97], v[96:97], v[216:217]
	v_pk_add_f32 v[98:99], v[98:99], v[216:217]
	v_rcp_f32_e32 v108, v108
	v_rcp_f32_e32 v109, v109
	v_rcp_f32_e32 v110, v110
	v_rcp_f32_e32 v111, v111
	v_rcp_f32_e32 v104, v104
	v_rcp_f32_e32 v105, v105
	v_rcp_f32_e32 v106, v106
	v_rcp_f32_e32 v107, v107
	v_rcp_f32_e32 v100, v100
	v_rcp_f32_e32 v101, v101
	v_rcp_f32_e32 v102, v102
	v_rcp_f32_e32 v103, v103
	v_rcp_f32_e32 v96, v96
	v_rcp_f32_e32 v97, v97
	v_rcp_f32_e32 v98, v98
	v_rcp_f32_e32 v99, v99
	s_nop 0
	v_cvt_pk_bf16_f32 v108, v108, v109
	v_cvt_pk_bf16_f32 v109, v110, v111
	v_cvt_pk_bf16_f32 v110, v104, v105
	v_cvt_pk_bf16_f32 v111, v106, v107
	global_store_dwordx4 v208, v[108:111], s[10:11]
	v_cvt_pk_bf16_f32 v100, v100, v101
	v_cvt_pk_bf16_f32 v101, v102, v103
	v_cvt_pk_bf16_f32 v102, v96, v97
	v_cvt_pk_bf16_f32 v103, v98, v99
	global_store_dwordx4 v208, v[100:103], s[10:11] offset:256
	v_pk_fma_f32 v[92:93], v[92:93], v[192:193], v[170:171] op_sel_hi:[1,0,1]
	v_pk_fma_f32 v[94:95], v[94:95], v[192:193], v[172:173] op_sel_hi:[1,0,1]
	v_pk_fma_f32 v[88:89], v[88:89], v[192:193], v[174:175] op_sel_hi:[1,0,1]
	v_pk_fma_f32 v[90:91], v[90:91], v[192:193], v[176:177] op_sel_hi:[1,0,1]
	v_pk_fma_f32 v[72:73], v[72:73], v[192:193], v[178:179] op_sel_hi:[1,0,1]
	v_pk_fma_f32 v[74:75], v[74:75], v[192:193], v[180:181] op_sel_hi:[1,0,1]
	v_pk_fma_f32 v[64:65], v[64:65], v[192:193], v[182:183] op_sel_hi:[1,0,1]
	v_pk_fma_f32 v[66:67], v[66:67], v[192:193], v[184:185] op_sel_hi:[1,0,1]
	v_exp_f32_e32 v92, v92
	v_exp_f32_e32 v93, v93
	v_exp_f32_e32 v94, v94
	v_exp_f32_e32 v95, v95
	v_exp_f32_e32 v88, v88
	v_exp_f32_e32 v89, v89
	v_exp_f32_e32 v90, v90
	v_exp_f32_e32 v91, v91
	v_exp_f32_e32 v72, v72
	v_exp_f32_e32 v73, v73
	v_exp_f32_e32 v74, v74
	v_exp_f32_e32 v75, v75
	v_exp_f32_e32 v64, v64
	v_exp_f32_e32 v65, v65
	v_exp_f32_e32 v66, v66
	v_exp_f32_e32 v67, v67
	s_nop 0
	v_pk_add_f32 v[92:93], v[92:93], v[216:217]
	v_pk_add_f32 v[94:95], v[94:95], v[216:217]
	v_pk_add_f32 v[88:89], v[88:89], v[216:217]
	v_pk_add_f32 v[90:91], v[90:91], v[216:217]
	v_pk_add_f32 v[72:73], v[72:73], v[216:217]
	v_pk_add_f32 v[74:75], v[74:75], v[216:217]
	v_pk_add_f32 v[64:65], v[64:65], v[216:217]
	v_pk_add_f32 v[66:67], v[66:67], v[216:217]
	v_rcp_f32_e32 v92, v92
	v_rcp_f32_e32 v93, v93
	v_rcp_f32_e32 v94, v94
	v_rcp_f32_e32 v95, v95
	v_rcp_f32_e32 v88, v88
	v_rcp_f32_e32 v89, v89
	v_rcp_f32_e32 v90, v90
	v_rcp_f32_e32 v91, v91
	v_rcp_f32_e32 v72, v72
	v_rcp_f32_e32 v73, v73
	v_rcp_f32_e32 v74, v74
	v_rcp_f32_e32 v75, v75
	v_rcp_f32_e32 v64, v64
	v_rcp_f32_e32 v65, v65
	v_rcp_f32_e32 v66, v66
	v_rcp_f32_e32 v67, v67
	s_nop 0
	v_cvt_pk_bf16_f32 v92, v92, v93
	v_cvt_pk_bf16_f32 v93, v94, v95
	v_cvt_pk_bf16_f32 v94, v88, v89
	v_cvt_pk_bf16_f32 v95, v90, v91
	global_store_dwordx4 v209, v[92:95], s[10:11]
	v_cvt_pk_bf16_f32 v72, v72, v73
	v_cvt_pk_bf16_f32 v73, v74, v75
	v_cvt_pk_bf16_f32 v74, v64, v65
	v_cvt_pk_bf16_f32 v75, v66, v67
	global_store_dwordx4 v209, v[72:75], s[10:11] offset:256
	v_pk_fma_f32 v[60:61], v[60:61], v[194:195], v[170:171] op_sel_hi:[1,0,1]
	v_pk_fma_f32 v[62:63], v[62:63], v[194:195], v[172:173] op_sel_hi:[1,0,1]
	v_pk_fma_f32 v[56:57], v[56:57], v[194:195], v[174:175] op_sel_hi:[1,0,1]
	v_pk_fma_f32 v[58:59], v[58:59], v[194:195], v[176:177] op_sel_hi:[1,0,1]
	v_pk_fma_f32 v[52:53], v[52:53], v[194:195], v[178:179] op_sel_hi:[1,0,1]
	v_pk_fma_f32 v[54:55], v[54:55], v[194:195], v[180:181] op_sel_hi:[1,0,1]
	v_pk_fma_f32 v[48:49], v[48:49], v[194:195], v[182:183] op_sel_hi:[1,0,1]
	v_pk_fma_f32 v[50:51], v[50:51], v[194:195], v[184:185] op_sel_hi:[1,0,1]
	v_exp_f32_e32 v60, v60
	v_exp_f32_e32 v61, v61
	v_exp_f32_e32 v62, v62
	v_exp_f32_e32 v63, v63
	v_exp_f32_e32 v56, v56
	v_exp_f32_e32 v57, v57
	v_exp_f32_e32 v58, v58
	v_exp_f32_e32 v59, v59
	v_exp_f32_e32 v52, v52
	v_exp_f32_e32 v53, v53
	v_exp_f32_e32 v54, v54
	v_exp_f32_e32 v55, v55
	v_exp_f32_e32 v48, v48
	v_exp_f32_e32 v49, v49
	v_exp_f32_e32 v50, v50
	v_exp_f32_e32 v51, v51
	s_nop 0
	v_pk_add_f32 v[60:61], v[60:61], v[216:217]
	v_pk_add_f32 v[62:63], v[62:63], v[216:217]
	v_pk_add_f32 v[56:57], v[56:57], v[216:217]
	v_pk_add_f32 v[58:59], v[58:59], v[216:217]
	v_pk_add_f32 v[52:53], v[52:53], v[216:217]
	v_pk_add_f32 v[54:55], v[54:55], v[216:217]
	v_pk_add_f32 v[48:49], v[48:49], v[216:217]
	v_pk_add_f32 v[50:51], v[50:51], v[216:217]
	v_rcp_f32_e32 v60, v60
	v_rcp_f32_e32 v61, v61
	v_rcp_f32_e32 v62, v62
	v_rcp_f32_e32 v63, v63
	v_rcp_f32_e32 v56, v56
	v_rcp_f32_e32 v57, v57
	v_rcp_f32_e32 v58, v58
	v_rcp_f32_e32 v59, v59
	v_rcp_f32_e32 v52, v52
	v_rcp_f32_e32 v53, v53
	v_rcp_f32_e32 v54, v54
	v_rcp_f32_e32 v55, v55
	v_rcp_f32_e32 v48, v48
	v_rcp_f32_e32 v49, v49
	v_rcp_f32_e32 v50, v50
	v_rcp_f32_e32 v51, v51
	s_nop 0
	v_cvt_pk_bf16_f32 v60, v60, v61
	v_cvt_pk_bf16_f32 v61, v62, v63
	v_cvt_pk_bf16_f32 v62, v56, v57
	v_cvt_pk_bf16_f32 v63, v58, v59
	global_store_dwordx4 v210, v[60:63], s[10:11]
	v_cvt_pk_bf16_f32 v52, v52, v53
	v_cvt_pk_bf16_f32 v53, v54, v55
	v_cvt_pk_bf16_f32 v54, v48, v49
	v_cvt_pk_bf16_f32 v55, v50, v51
	global_store_dwordx4 v210, v[52:55], s[10:11] offset:256
	v_pk_fma_f32 v[44:45], v[44:45], v[196:197], v[170:171] op_sel_hi:[1,0,1]
	v_pk_fma_f32 v[46:47], v[46:47], v[196:197], v[172:173] op_sel_hi:[1,0,1]
	v_pk_fma_f32 v[40:41], v[40:41], v[196:197], v[174:175] op_sel_hi:[1,0,1]
	v_pk_fma_f32 v[42:43], v[42:43], v[196:197], v[176:177] op_sel_hi:[1,0,1]
	v_pk_fma_f32 v[36:37], v[36:37], v[196:197], v[178:179] op_sel_hi:[1,0,1]
	v_pk_fma_f32 v[38:39], v[38:39], v[196:197], v[180:181] op_sel_hi:[1,0,1]
	v_pk_fma_f32 v[32:33], v[32:33], v[196:197], v[182:183] op_sel_hi:[1,0,1]
	v_pk_fma_f32 v[34:35], v[34:35], v[196:197], v[184:185] op_sel_hi:[1,0,1]
	v_exp_f32_e32 v44, v44
	v_exp_f32_e32 v45, v45
	v_exp_f32_e32 v46, v46
	v_exp_f32_e32 v47, v47
	v_exp_f32_e32 v40, v40
	v_exp_f32_e32 v41, v41
	v_exp_f32_e32 v42, v42
	v_exp_f32_e32 v43, v43
	v_exp_f32_e32 v36, v36
	v_exp_f32_e32 v37, v37
	v_exp_f32_e32 v38, v38
	v_exp_f32_e32 v39, v39
	v_exp_f32_e32 v32, v32
	v_exp_f32_e32 v33, v33
	v_exp_f32_e32 v34, v34
	v_exp_f32_e32 v35, v35
	s_nop 0
	v_pk_add_f32 v[44:45], v[44:45], v[216:217]
	v_pk_add_f32 v[46:47], v[46:47], v[216:217]
	v_pk_add_f32 v[40:41], v[40:41], v[216:217]
	v_pk_add_f32 v[42:43], v[42:43], v[216:217]
	v_pk_add_f32 v[36:37], v[36:37], v[216:217]
	v_pk_add_f32 v[38:39], v[38:39], v[216:217]
	v_pk_add_f32 v[32:33], v[32:33], v[216:217]
	v_pk_add_f32 v[34:35], v[34:35], v[216:217]
	v_rcp_f32_e32 v44, v44
	v_rcp_f32_e32 v45, v45
	v_rcp_f32_e32 v46, v46
	v_rcp_f32_e32 v47, v47
	v_rcp_f32_e32 v40, v40
	v_rcp_f32_e32 v41, v41
	v_rcp_f32_e32 v42, v42
	v_rcp_f32_e32 v43, v43
	v_rcp_f32_e32 v36, v36
	v_rcp_f32_e32 v37, v37
	v_rcp_f32_e32 v38, v38
	v_rcp_f32_e32 v39, v39
	v_rcp_f32_e32 v32, v32
	v_rcp_f32_e32 v33, v33
	v_rcp_f32_e32 v34, v34
	v_rcp_f32_e32 v35, v35
	s_nop 0
	v_cvt_pk_bf16_f32 v44, v44, v45
	v_cvt_pk_bf16_f32 v45, v46, v47
	v_cvt_pk_bf16_f32 v46, v40, v41
	v_cvt_pk_bf16_f32 v47, v42, v43
	global_store_dwordx4 v211, v[44:47], s[10:11]
	v_cvt_pk_bf16_f32 v36, v36, v37
	v_cvt_pk_bf16_f32 v37, v38, v39
	v_cvt_pk_bf16_f32 v38, v32, v33
	v_cvt_pk_bf16_f32 v39, v34, v35
	global_store_dwordx4 v211, v[36:39], s[10:11] offset:256
	v_pk_fma_f32 v[28:29], v[28:29], v[198:199], v[170:171] op_sel_hi:[1,0,1]
	v_pk_fma_f32 v[30:31], v[30:31], v[198:199], v[172:173] op_sel_hi:[1,0,1]
	v_pk_fma_f32 v[24:25], v[24:25], v[198:199], v[174:175] op_sel_hi:[1,0,1]
	v_pk_fma_f32 v[26:27], v[26:27], v[198:199], v[176:177] op_sel_hi:[1,0,1]
	v_pk_fma_f32 v[20:21], v[20:21], v[198:199], v[178:179] op_sel_hi:[1,0,1]
	v_pk_fma_f32 v[22:23], v[22:23], v[198:199], v[180:181] op_sel_hi:[1,0,1]
	v_pk_fma_f32 v[16:17], v[16:17], v[198:199], v[182:183] op_sel_hi:[1,0,1]
	v_pk_fma_f32 v[18:19], v[18:19], v[198:199], v[184:185] op_sel_hi:[1,0,1]
	v_exp_f32_e32 v28, v28
	v_exp_f32_e32 v29, v29
	v_exp_f32_e32 v30, v30
	v_exp_f32_e32 v31, v31
	v_exp_f32_e32 v24, v24
	v_exp_f32_e32 v25, v25
	v_exp_f32_e32 v26, v26
	v_exp_f32_e32 v27, v27
	v_exp_f32_e32 v20, v20
	v_exp_f32_e32 v21, v21
	v_exp_f32_e32 v22, v22
	v_exp_f32_e32 v23, v23
	v_exp_f32_e32 v16, v16
	v_exp_f32_e32 v17, v17
	v_exp_f32_e32 v18, v18
	v_exp_f32_e32 v19, v19
	s_nop 0
	v_pk_add_f32 v[28:29], v[28:29], v[216:217]
	v_pk_add_f32 v[30:31], v[30:31], v[216:217]
	v_pk_add_f32 v[24:25], v[24:25], v[216:217]
	v_pk_add_f32 v[26:27], v[26:27], v[216:217]
	v_pk_add_f32 v[20:21], v[20:21], v[216:217]
	v_pk_add_f32 v[22:23], v[22:23], v[216:217]
	v_pk_add_f32 v[16:17], v[16:17], v[216:217]
	v_pk_add_f32 v[18:19], v[18:19], v[216:217]
	v_rcp_f32_e32 v28, v28
	v_rcp_f32_e32 v29, v29
	v_rcp_f32_e32 v30, v30
	v_rcp_f32_e32 v31, v31
	v_rcp_f32_e32 v24, v24
	v_rcp_f32_e32 v25, v25
	v_rcp_f32_e32 v26, v26
	v_rcp_f32_e32 v27, v27
	v_rcp_f32_e32 v20, v20
	v_rcp_f32_e32 v21, v21
	v_rcp_f32_e32 v22, v22
	v_rcp_f32_e32 v23, v23
	v_rcp_f32_e32 v16, v16
	v_rcp_f32_e32 v17, v17
	v_rcp_f32_e32 v18, v18
	v_rcp_f32_e32 v19, v19
	s_nop 0
	v_cvt_pk_bf16_f32 v28, v28, v29
	v_cvt_pk_bf16_f32 v29, v30, v31
	v_cvt_pk_bf16_f32 v30, v24, v25
	v_cvt_pk_bf16_f32 v31, v26, v27
	global_store_dwordx4 v212, v[28:31], s[10:11]
	v_cvt_pk_bf16_f32 v20, v20, v21
	v_cvt_pk_bf16_f32 v21, v22, v23
	v_cvt_pk_bf16_f32 v22, v16, v17
	v_cvt_pk_bf16_f32 v23, v18, v19
	global_store_dwordx4 v212, v[20:23], s[10:11] offset:256
	v_pk_fma_f32 v[12:13], v[12:13], v[200:201], v[170:171] op_sel_hi:[1,0,1]
	v_pk_fma_f32 v[14:15], v[14:15], v[200:201], v[172:173] op_sel_hi:[1,0,1]
	v_pk_fma_f32 v[8:9], v[8:9], v[200:201], v[174:175] op_sel_hi:[1,0,1]
	v_pk_fma_f32 v[10:11], v[10:11], v[200:201], v[176:177] op_sel_hi:[1,0,1]
	v_pk_fma_f32 v[4:5], v[4:5], v[200:201], v[178:179] op_sel_hi:[1,0,1]
	v_pk_fma_f32 v[6:7], v[6:7], v[200:201], v[180:181] op_sel_hi:[1,0,1]
	v_pk_fma_f32 v[0:1], v[0:1], v[200:201], v[182:183] op_sel_hi:[1,0,1]
	v_pk_fma_f32 v[2:3], v[2:3], v[200:201], v[184:185] op_sel_hi:[1,0,1]
	v_exp_f32_e32 v12, v12
	v_exp_f32_e32 v13, v13
	v_exp_f32_e32 v14, v14
	v_exp_f32_e32 v15, v15
	v_exp_f32_e32 v8, v8
	v_exp_f32_e32 v9, v9
	v_exp_f32_e32 v10, v10
	v_exp_f32_e32 v11, v11
	v_exp_f32_e32 v4, v4
	v_exp_f32_e32 v5, v5
	v_exp_f32_e32 v6, v6
	v_exp_f32_e32 v7, v7
	v_exp_f32_e32 v0, v0
	v_exp_f32_e32 v1, v1
	v_exp_f32_e32 v2, v2
	v_exp_f32_e32 v3, v3
	s_nop 0
	v_pk_add_f32 v[12:13], v[12:13], v[216:217]
	v_pk_add_f32 v[14:15], v[14:15], v[216:217]
	v_pk_add_f32 v[8:9], v[8:9], v[216:217]
	v_pk_add_f32 v[10:11], v[10:11], v[216:217]
	v_pk_add_f32 v[4:5], v[4:5], v[216:217]
	v_pk_add_f32 v[6:7], v[6:7], v[216:217]
	v_pk_add_f32 v[0:1], v[0:1], v[216:217]
	v_pk_add_f32 v[2:3], v[2:3], v[216:217]
	v_rcp_f32_e32 v12, v12
	v_rcp_f32_e32 v13, v13
	v_rcp_f32_e32 v14, v14
	v_rcp_f32_e32 v15, v15
	v_rcp_f32_e32 v8, v8
	v_rcp_f32_e32 v9, v9
	v_rcp_f32_e32 v10, v10
	v_rcp_f32_e32 v11, v11
	v_rcp_f32_e32 v4, v4
	v_rcp_f32_e32 v5, v5
	v_rcp_f32_e32 v6, v6
	v_rcp_f32_e32 v7, v7
	v_rcp_f32_e32 v0, v0
	v_rcp_f32_e32 v1, v1
	v_rcp_f32_e32 v2, v2
	v_rcp_f32_e32 v3, v3
	s_nop 0
	v_cvt_pk_bf16_f32 v12, v12, v13
	v_cvt_pk_bf16_f32 v13, v14, v15
	v_cvt_pk_bf16_f32 v14, v8, v9
	v_cvt_pk_bf16_f32 v15, v10, v11
	global_store_dwordx4 v213, v[12:15], s[10:11]
	v_cvt_pk_bf16_f32 v4, v4, v5
	v_cvt_pk_bf16_f32 v5, v6, v7
	v_cvt_pk_bf16_f32 v6, v0, v1
	v_cvt_pk_bf16_f32 v7, v2, v3
	global_store_dwordx4 v213, v[4:7], s[10:11] offset:256
	s_andn2_b64 vcc, exec, s[4:5]
	s_mov_b64 s[4:5], -1
	s_cbranch_vccnz .LBB0_1047
	s_and_b64 vcc, exec, s[0:1]
	s_cbranch_vccnz .LBB0_1046
	s_barrier
	s_branch .LBB0_1046

.LBB0_1098:
	v_lshl_add_u32 v202, s63, 8, v166
	v_lshl_add_u32 v203, s34, 8, v164
	v_lshlrev_b32_e32 v204, 12, v203
	v_lshl_add_u32 v204, v202, 1, v204
	v_lshlrev_b32_e32 v202, 2, v202
	v_lshlrev_b32_e32 v203, 2, v203
	global_load_dwordx4 v[170:173], v202, s[16:17]
	global_load_dwordx4 v[174:177], v202, s[16:17] offset:16
	global_load_dwordx4 v[178:181], v202, s[16:17] offset:512
	global_load_dwordx4 v[182:185], v202, s[16:17] offset:528
	global_load_dword v186, v203, s[24:25]
	global_load_dword v188, v203, s[24:25] offset:64
	global_load_dword v190, v203, s[24:25] offset:128
	global_load_dword v192, v203, s[24:25] offset:192
	global_load_dword v194, v203, s[24:25] offset:512
	global_load_dword v196, v203, s[24:25] offset:576
	global_load_dword v198, v203, s[24:25] offset:640
	global_load_dword v200, v203, s[24:25] offset:704
	v_mov_b32_e32 v214, 0xbfb8aa3b
	v_mov_b32_e32 v215, 0xbfb8aa3b
	v_mov_b32_e32 v216, 1.0
	v_mov_b32_e32 v217, 1.0
	v_mov_b32_e32 v206, v204
	v_add_u32_e32 v207, 0x10000, v204
	v_add_u32_e32 v208, 0x20000, v204
	v_add_u32_e32 v209, 0x30000, v204
	v_add_u32_e32 v210, 0x80000, v204
	v_add_u32_e32 v211, 0x90000, v204
	v_add_u32_e32 v212, 0xa0000, v204
	v_add_u32_e32 v213, 0xb0000, v204
	s_waitcnt vmcnt(0)
	v_pk_mul_f32 v[170:171], v[170:171], v[214:215]
	v_pk_mul_f32 v[172:173], v[172:173], v[214:215]
	v_pk_mul_f32 v[174:175], v[174:175], v[214:215]
	v_pk_mul_f32 v[176:177], v[176:177], v[214:215]
	v_pk_mul_f32 v[178:179], v[178:179], v[214:215]
	v_pk_mul_f32 v[180:181], v[180:181], v[214:215]
	v_pk_mul_f32 v[182:183], v[182:183], v[214:215]
	v_pk_mul_f32 v[184:185], v[184:185], v[214:215]
	v_mul_f32_e32 v186, 0xbfb8aa3b, v186
	v_mul_f32_e32 v188, 0xbfb8aa3b, v188
	v_mul_f32_e32 v190, 0xbfb8aa3b, v190
	v_mul_f32_e32 v192, 0xbfb8aa3b, v192
	v_mul_f32_e32 v194, 0xbfb8aa3b, v194
	v_mul_f32_e32 v196, 0xbfb8aa3b, v196
	v_mul_f32_e32 v198, 0xbfb8aa3b, v198
	v_mul_f32_e32 v200, 0xbfb8aa3b, v200
	v_pk_fma_f32 v[140:141], v[140:141], v[186:187], v[170:171] op_sel_hi:[1,0,1]
	v_pk_fma_f32 v[142:143], v[142:143], v[186:187], v[172:173] op_sel_hi:[1,0,1]
	v_pk_fma_f32 v[136:137], v[136:137], v[186:187], v[174:175] op_sel_hi:[1,0,1]
	v_pk_fma_f32 v[138:139], v[138:139], v[186:187], v[176:177] op_sel_hi:[1,0,1]
	v_pk_fma_f32 v[132:133], v[132:133], v[186:187], v[178:179] op_sel_hi:[1,0,1]
	v_pk_fma_f32 v[134:135], v[134:135], v[186:187], v[180:181] op_sel_hi:[1,0,1]
	v_pk_fma_f32 v[128:129], v[128:129], v[186:187], v[182:183] op_sel_hi:[1,0,1]
	v_pk_fma_f32 v[130:131], v[130:131], v[186:187], v[184:185] op_sel_hi:[1,0,1]
	v_exp_f32_e32 v140, v140
	v_exp_f32_e32 v141, v141
	v_exp_f32_e32 v142, v142
	v_exp_f32_e32 v143, v143
	v_exp_f32_e32 v136, v136
	v_exp_f32_e32 v137, v137
	v_exp_f32_e32 v138, v138
	v_exp_f32_e32 v139, v139
	v_exp_f32_e32 v132, v132
	v_exp_f32_e32 v133, v133
	v_exp_f32_e32 v134, v134
	v_exp_f32_e32 v135, v135
	v_exp_f32_e32 v128, v128
	v_exp_f32_e32 v129, v129
	v_exp_f32_e32 v130, v130
	v_exp_f32_e32 v131, v131
	s_nop 0
	v_pk_add_f32 v[140:141], v[140:141], v[216:217]
	v_pk_add_f32 v[142:143], v[142:143], v[216:217]
	v_pk_add_f32 v[136:137], v[136:137], v[216:217]
	v_pk_add_f32 v[138:139], v[138:139], v[216:217]
	v_pk_add_f32 v[132:133], v[132:133], v[216:217]
	v_pk_add_f32 v[134:135], v[134:135], v[216:217]
	v_pk_add_f32 v[128:129], v[128:129], v[216:217]
	v_pk_add_f32 v[130:131], v[130:131], v[216:217]
	v_rcp_f32_e32 v140, v140
	v_rcp_f32_e32 v141, v141
	v_rcp_f32_e32 v142, v142
	v_rcp_f32_e32 v143, v143
	v_rcp_f32_e32 v136, v136
	v_rcp_f32_e32 v137, v137
	v_rcp_f32_e32 v138, v138
	v_rcp_f32_e32 v139, v139
	v_rcp_f32_e32 v132, v132
	v_rcp_f32_e32 v133, v133
	v_rcp_f32_e32 v134, v134
	v_rcp_f32_e32 v135, v135
	v_rcp_f32_e32 v128, v128
	v_rcp_f32_e32 v129, v129
	v_rcp_f32_e32 v130, v130
	v_rcp_f32_e32 v131, v131
	s_nop 0
	v_cvt_pk_bf16_f32 v140, v140, v141
	v_cvt_pk_bf16_f32 v141, v142, v143
	v_cvt_pk_bf16_f32 v142, v136, v137
	v_cvt_pk_bf16_f32 v143, v138, v139
	global_store_dwordx4 v206, v[140:143], s[10:11]
	v_cvt_pk_bf16_f32 v132, v132, v133
	v_cvt_pk_bf16_f32 v133, v134, v135
	v_cvt_pk_bf16_f32 v134, v128, v129
	v_cvt_pk_bf16_f32 v135, v130, v131
	global_store_dwordx4 v206, v[132:135], s[10:11] offset:256
	v_pk_fma_f32 v[124:125], v[124:125], v[188:189], v[170:171] op_sel_hi:[1,0,1]
	v_pk_fma_f32 v[126:127], v[126:127], v[188:189], v[172:173] op_sel_hi:[1,0,1]
	v_pk_fma_f32 v[120:121], v[120:121], v[188:189], v[174:175] op_sel_hi:[1,0,1]
	v_pk_fma_f32 v[122:123], v[122:123], v[188:189], v[176:177] op_sel_hi:[1,0,1]
	v_pk_fma_f32 v[116:117], v[116:117], v[188:189], v[178:179] op_sel_hi:[1,0,1]
	v_pk_fma_f32 v[118:119], v[118:119], v[188:189], v[180:181] op_sel_hi:[1,0,1]
	v_pk_fma_f32 v[112:113], v[112:113], v[188:189], v[182:183] op_sel_hi:[1,0,1]
	v_pk_fma_f32 v[114:115], v[114:115], v[188:189], v[184:185] op_sel_hi:[1,0,1]
	v_exp_f32_e32 v124, v124
	v_exp_f32_e32 v125, v125
	v_exp_f32_e32 v126, v126
	v_exp_f32_e32 v127, v127
	v_exp_f32_e32 v120, v120
	v_exp_f32_e32 v121, v121
	v_exp_f32_e32 v122, v122
	v_exp_f32_e32 v123, v123
	v_exp_f32_e32 v116, v116
	v_exp_f32_e32 v117, v117
	v_exp_f32_e32 v118, v118
	v_exp_f32_e32 v119, v119
	v_exp_f32_e32 v112, v112
	v_exp_f32_e32 v113, v113
	v_exp_f32_e32 v114, v114
	v_exp_f32_e32 v115, v115
	s_nop 0
	v_pk_add_f32 v[124:125], v[124:125], v[216:217]
	v_pk_add_f32 v[126:127], v[126:127], v[216:217]
	v_pk_add_f32 v[120:121], v[120:121], v[216:217]
	v_pk_add_f32 v[122:123], v[122:123], v[216:217]
	v_pk_add_f32 v[116:117], v[116:117], v[216:217]
	v_pk_add_f32 v[118:119], v[118:119], v[216:217]
	v_pk_add_f32 v[112:113], v[112:113], v[216:217]
	v_pk_add_f32 v[114:115], v[114:115], v[216:217]
	v_rcp_f32_e32 v124, v124
	v_rcp_f32_e32 v125, v125
	v_rcp_f32_e32 v126, v126
	v_rcp_f32_e32 v127, v127
	v_rcp_f32_e32 v120, v120
	v_rcp_f32_e32 v121, v121
	v_rcp_f32_e32 v122, v122
	v_rcp_f32_e32 v123, v123
	v_rcp_f32_e32 v116, v116
	v_rcp_f32_e32 v117, v117
	v_rcp_f32_e32 v118, v118
	v_rcp_f32_e32 v119, v119
	v_rcp_f32_e32 v112, v112
	v_rcp_f32_e32 v113, v113
	v_rcp_f32_e32 v114, v114
	v_rcp_f32_e32 v115, v115
	s_nop 0
	v_cvt_pk_bf16_f32 v124, v124, v125
	v_cvt_pk_bf16_f32 v125, v126, v127
	v_cvt_pk_bf16_f32 v126, v120, v121
	v_cvt_pk_bf16_f32 v127, v122, v123
	global_store_dwordx4 v207, v[124:127], s[10:11]
	v_cvt_pk_bf16_f32 v116, v116, v117
	v_cvt_pk_bf16_f32 v117, v118, v119
	v_cvt_pk_bf16_f32 v118, v112, v113
	v_cvt_pk_bf16_f32 v119, v114, v115
	global_store_dwordx4 v207, v[116:119], s[10:11] offset:256
	v_pk_fma_f32 v[108:109], v[108:109], v[190:191], v[170:171] op_sel_hi:[1,0,1]
	v_pk_fma_f32 v[110:111], v[110:111], v[190:191], v[172:173] op_sel_hi:[1,0,1]
	v_pk_fma_f32 v[104:105], v[104:105], v[190:191], v[174:175] op_sel_hi:[1,0,1]
	v_pk_fma_f32 v[106:107], v[106:107], v[190:191], v[176:177] op_sel_hi:[1,0,1]
	v_pk_fma_f32 v[100:101], v[100:101], v[190:191], v[178:179] op_sel_hi:[1,0,1]
	v_pk_fma_f32 v[102:103], v[102:103], v[190:191], v[180:181] op_sel_hi:[1,0,1]
	v_pk_fma_f32 v[96:97], v[96:97], v[190:191], v[182:183] op_sel_hi:[1,0,1]
	v_pk_fma_f32 v[98:99], v[98:99], v[190:191], v[184:185] op_sel_hi:[1,0,1]
	v_exp_f32_e32 v108, v108
	v_exp_f32_e32 v109, v109
	v_exp_f32_e32 v110, v110
	v_exp_f32_e32 v111, v111
	v_exp_f32_e32 v104, v104
	v_exp_f32_e32 v105, v105
	v_exp_f32_e32 v106, v106
	v_exp_f32_e32 v107, v107
	v_exp_f32_e32 v100, v100
	v_exp_f32_e32 v101, v101
	v_exp_f32_e32 v102, v102
	v_exp_f32_e32 v103, v103
	v_exp_f32_e32 v96, v96
	v_exp_f32_e32 v97, v97
	v_exp_f32_e32 v98, v98
	v_exp_f32_e32 v99, v99
	s_nop 0
	v_pk_add_f32 v[108:109], v[108:109], v[216:217]
	v_pk_add_f32 v[110:111], v[110:111], v[216:217]
	v_pk_add_f32 v[104:105], v[104:105], v[216:217]
	v_pk_add_f32 v[106:107], v[106:107], v[216:217]
	v_pk_add_f32 v[100:101], v[100:101], v[216:217]
	v_pk_add_f32 v[102:103], v[102:103], v[216:217]
	v_pk_add_f32 v[96:97], v[96:97], v[216:217]
	v_pk_add_f32 v[98:99], v[98:99], v[216:217]
	v_rcp_f32_e32 v108, v108
	v_rcp_f32_e32 v109, v109
	v_rcp_f32_e32 v110, v110
	v_rcp_f32_e32 v111, v111
	v_rcp_f32_e32 v104, v104
	v_rcp_f32_e32 v105, v105
	v_rcp_f32_e32 v106, v106
	v_rcp_f32_e32 v107, v107
	v_rcp_f32_e32 v100, v100
	v_rcp_f32_e32 v101, v101
	v_rcp_f32_e32 v102, v102
	v_rcp_f32_e32 v103, v103
	v_rcp_f32_e32 v96, v96
	v_rcp_f32_e32 v97, v97
	v_rcp_f32_e32 v98, v98
	v_rcp_f32_e32 v99, v99
	s_nop 0
	v_cvt_pk_bf16_f32 v108, v108, v109
	v_cvt_pk_bf16_f32 v109, v110, v111
	v_cvt_pk_bf16_f32 v110, v104, v105
	v_cvt_pk_bf16_f32 v111, v106, v107
	global_store_dwordx4 v208, v[108:111], s[10:11]
	v_cvt_pk_bf16_f32 v100, v100, v101
	v_cvt_pk_bf16_f32 v101, v102, v103
	v_cvt_pk_bf16_f32 v102, v96, v97
	v_cvt_pk_bf16_f32 v103, v98, v99
	global_store_dwordx4 v208, v[100:103], s[10:11] offset:256
	v_pk_fma_f32 v[92:93], v[92:93], v[192:193], v[170:171] op_sel_hi:[1,0,1]
	v_pk_fma_f32 v[94:95], v[94:95], v[192:193], v[172:173] op_sel_hi:[1,0,1]
	v_pk_fma_f32 v[88:89], v[88:89], v[192:193], v[174:175] op_sel_hi:[1,0,1]
	v_pk_fma_f32 v[90:91], v[90:91], v[192:193], v[176:177] op_sel_hi:[1,0,1]
	v_pk_fma_f32 v[72:73], v[72:73], v[192:193], v[178:179] op_sel_hi:[1,0,1]
	v_pk_fma_f32 v[74:75], v[74:75], v[192:193], v[180:181] op_sel_hi:[1,0,1]
	v_pk_fma_f32 v[64:65], v[64:65], v[192:193], v[182:183] op_sel_hi:[1,0,1]
	v_pk_fma_f32 v[66:67], v[66:67], v[192:193], v[184:185] op_sel_hi:[1,0,1]
	v_exp_f32_e32 v92, v92
	v_exp_f32_e32 v93, v93
	v_exp_f32_e32 v94, v94
	v_exp_f32_e32 v95, v95
	v_exp_f32_e32 v88, v88
	v_exp_f32_e32 v89, v89
	v_exp_f32_e32 v90, v90
	v_exp_f32_e32 v91, v91
	v_exp_f32_e32 v72, v72
	v_exp_f32_e32 v73, v73
	v_exp_f32_e32 v74, v74
	v_exp_f32_e32 v75, v75
	v_exp_f32_e32 v64, v64
	v_exp_f32_e32 v65, v65
	v_exp_f32_e32 v66, v66
	v_exp_f32_e32 v67, v67
	s_nop 0
	v_pk_add_f32 v[92:93], v[92:93], v[216:217]
	v_pk_add_f32 v[94:95], v[94:95], v[216:217]
	v_pk_add_f32 v[88:89], v[88:89], v[216:217]
	v_pk_add_f32 v[90:91], v[90:91], v[216:217]
	v_pk_add_f32 v[72:73], v[72:73], v[216:217]
	v_pk_add_f32 v[74:75], v[74:75], v[216:217]
	v_pk_add_f32 v[64:65], v[64:65], v[216:217]
	v_pk_add_f32 v[66:67], v[66:67], v[216:217]
	v_rcp_f32_e32 v92, v92
	v_rcp_f32_e32 v93, v93
	v_rcp_f32_e32 v94, v94
	v_rcp_f32_e32 v95, v95
	v_rcp_f32_e32 v88, v88
	v_rcp_f32_e32 v89, v89
	v_rcp_f32_e32 v90, v90
	v_rcp_f32_e32 v91, v91
	v_rcp_f32_e32 v72, v72
	v_rcp_f32_e32 v73, v73
	v_rcp_f32_e32 v74, v74
	v_rcp_f32_e32 v75, v75
	v_rcp_f32_e32 v64, v64
	v_rcp_f32_e32 v65, v65
	v_rcp_f32_e32 v66, v66
	v_rcp_f32_e32 v67, v67
	s_nop 0
	v_cvt_pk_bf16_f32 v92, v92, v93
	v_cvt_pk_bf16_f32 v93, v94, v95
	v_cvt_pk_bf16_f32 v94, v88, v89
	v_cvt_pk_bf16_f32 v95, v90, v91
	global_store_dwordx4 v209, v[92:95], s[10:11]
	v_cvt_pk_bf16_f32 v72, v72, v73
	v_cvt_pk_bf16_f32 v73, v74, v75
	v_cvt_pk_bf16_f32 v74, v64, v65
	v_cvt_pk_bf16_f32 v75, v66, v67
	global_store_dwordx4 v209, v[72:75], s[10:11] offset:256
	v_pk_fma_f32 v[60:61], v[60:61], v[194:195], v[170:171] op_sel_hi:[1,0,1]
	v_pk_fma_f32 v[62:63], v[62:63], v[194:195], v[172:173] op_sel_hi:[1,0,1]
	v_pk_fma_f32 v[56:57], v[56:57], v[194:195], v[174:175] op_sel_hi:[1,0,1]
	v_pk_fma_f32 v[58:59], v[58:59], v[194:195], v[176:177] op_sel_hi:[1,0,1]
	v_pk_fma_f32 v[52:53], v[52:53], v[194:195], v[178:179] op_sel_hi:[1,0,1]
	v_pk_fma_f32 v[54:55], v[54:55], v[194:195], v[180:181] op_sel_hi:[1,0,1]
	v_pk_fma_f32 v[48:49], v[48:49], v[194:195], v[182:183] op_sel_hi:[1,0,1]
	v_pk_fma_f32 v[50:51], v[50:51], v[194:195], v[184:185] op_sel_hi:[1,0,1]
	v_exp_f32_e32 v60, v60
	v_exp_f32_e32 v61, v61
	v_exp_f32_e32 v62, v62
	v_exp_f32_e32 v63, v63
	v_exp_f32_e32 v56, v56
	v_exp_f32_e32 v57, v57
	v_exp_f32_e32 v58, v58
	v_exp_f32_e32 v59, v59
	v_exp_f32_e32 v52, v52
	v_exp_f32_e32 v53, v53
	v_exp_f32_e32 v54, v54
	v_exp_f32_e32 v55, v55
	v_exp_f32_e32 v48, v48
	v_exp_f32_e32 v49, v49
	v_exp_f32_e32 v50, v50
	v_exp_f32_e32 v51, v51
	s_nop 0
	v_pk_add_f32 v[60:61], v[60:61], v[216:217]
	v_pk_add_f32 v[62:63], v[62:63], v[216:217]
	v_pk_add_f32 v[56:57], v[56:57], v[216:217]
	v_pk_add_f32 v[58:59], v[58:59], v[216:217]
	v_pk_add_f32 v[52:53], v[52:53], v[216:217]
	v_pk_add_f32 v[54:55], v[54:55], v[216:217]
	v_pk_add_f32 v[48:49], v[48:49], v[216:217]
	v_pk_add_f32 v[50:51], v[50:51], v[216:217]
	v_rcp_f32_e32 v60, v60
	v_rcp_f32_e32 v61, v61
	v_rcp_f32_e32 v62, v62
	v_rcp_f32_e32 v63, v63
	v_rcp_f32_e32 v56, v56
	v_rcp_f32_e32 v57, v57
	v_rcp_f32_e32 v58, v58
	v_rcp_f32_e32 v59, v59
	v_rcp_f32_e32 v52, v52
	v_rcp_f32_e32 v53, v53
	v_rcp_f32_e32 v54, v54
	v_rcp_f32_e32 v55, v55
	v_rcp_f32_e32 v48, v48
	v_rcp_f32_e32 v49, v49
	v_rcp_f32_e32 v50, v50
	v_rcp_f32_e32 v51, v51
	s_nop 0
	v_cvt_pk_bf16_f32 v60, v60, v61
	v_cvt_pk_bf16_f32 v61, v62, v63
	v_cvt_pk_bf16_f32 v62, v56, v57
	v_cvt_pk_bf16_f32 v63, v58, v59
	global_store_dwordx4 v210, v[60:63], s[10:11]
	v_cvt_pk_bf16_f32 v52, v52, v53
	v_cvt_pk_bf16_f32 v53, v54, v55
	v_cvt_pk_bf16_f32 v54, v48, v49
	v_cvt_pk_bf16_f32 v55, v50, v51
	global_store_dwordx4 v210, v[52:55], s[10:11] offset:256
	v_pk_fma_f32 v[44:45], v[44:45], v[196:197], v[170:171] op_sel_hi:[1,0,1]
	v_pk_fma_f32 v[46:47], v[46:47], v[196:197], v[172:173] op_sel_hi:[1,0,1]
	v_pk_fma_f32 v[40:41], v[40:41], v[196:197], v[174:175] op_sel_hi:[1,0,1]
	v_pk_fma_f32 v[42:43], v[42:43], v[196:197], v[176:177] op_sel_hi:[1,0,1]
	v_pk_fma_f32 v[36:37], v[36:37], v[196:197], v[178:179] op_sel_hi:[1,0,1]
	v_pk_fma_f32 v[38:39], v[38:39], v[196:197], v[180:181] op_sel_hi:[1,0,1]
	v_pk_fma_f32 v[32:33], v[32:33], v[196:197], v[182:183] op_sel_hi:[1,0,1]
	v_pk_fma_f32 v[34:35], v[34:35], v[196:197], v[184:185] op_sel_hi:[1,0,1]
	v_exp_f32_e32 v44, v44
	v_exp_f32_e32 v45, v45
	v_exp_f32_e32 v46, v46
	v_exp_f32_e32 v47, v47
	v_exp_f32_e32 v40, v40
	v_exp_f32_e32 v41, v41
	v_exp_f32_e32 v42, v42
	v_exp_f32_e32 v43, v43
	v_exp_f32_e32 v36, v36
	v_exp_f32_e32 v37, v37
	v_exp_f32_e32 v38, v38
	v_exp_f32_e32 v39, v39
	v_exp_f32_e32 v32, v32
	v_exp_f32_e32 v33, v33
	v_exp_f32_e32 v34, v34
	v_exp_f32_e32 v35, v35
	s_nop 0
	v_pk_add_f32 v[44:45], v[44:45], v[216:217]
	v_pk_add_f32 v[46:47], v[46:47], v[216:217]
	v_pk_add_f32 v[40:41], v[40:41], v[216:217]
	v_pk_add_f32 v[42:43], v[42:43], v[216:217]
	v_pk_add_f32 v[36:37], v[36:37], v[216:217]
	v_pk_add_f32 v[38:39], v[38:39], v[216:217]
	v_pk_add_f32 v[32:33], v[32:33], v[216:217]
	v_pk_add_f32 v[34:35], v[34:35], v[216:217]
	v_rcp_f32_e32 v44, v44
	v_rcp_f32_e32 v45, v45
	v_rcp_f32_e32 v46, v46
	v_rcp_f32_e32 v47, v47
	v_rcp_f32_e32 v40, v40
	v_rcp_f32_e32 v41, v41
	v_rcp_f32_e32 v42, v42
	v_rcp_f32_e32 v43, v43
	v_rcp_f32_e32 v36, v36
	v_rcp_f32_e32 v37, v37
	v_rcp_f32_e32 v38, v38
	v_rcp_f32_e32 v39, v39
	v_rcp_f32_e32 v32, v32
	v_rcp_f32_e32 v33, v33
	v_rcp_f32_e32 v34, v34
	v_rcp_f32_e32 v35, v35
	s_nop 0
	v_cvt_pk_bf16_f32 v44, v44, v45
	v_cvt_pk_bf16_f32 v45, v46, v47
	v_cvt_pk_bf16_f32 v46, v40, v41
	v_cvt_pk_bf16_f32 v47, v42, v43
	global_store_dwordx4 v211, v[44:47], s[10:11]
	v_cvt_pk_bf16_f32 v36, v36, v37
	v_cvt_pk_bf16_f32 v37, v38, v39
	v_cvt_pk_bf16_f32 v38, v32, v33
	v_cvt_pk_bf16_f32 v39, v34, v35
	global_store_dwordx4 v211, v[36:39], s[10:11] offset:256
	v_pk_fma_f32 v[28:29], v[28:29], v[198:199], v[170:171] op_sel_hi:[1,0,1]
	v_pk_fma_f32 v[30:31], v[30:31], v[198:199], v[172:173] op_sel_hi:[1,0,1]
	v_pk_fma_f32 v[24:25], v[24:25], v[198:199], v[174:175] op_sel_hi:[1,0,1]
	v_pk_fma_f32 v[26:27], v[26:27], v[198:199], v[176:177] op_sel_hi:[1,0,1]
	v_pk_fma_f32 v[20:21], v[20:21], v[198:199], v[178:179] op_sel_hi:[1,0,1]
	v_pk_fma_f32 v[22:23], v[22:23], v[198:199], v[180:181] op_sel_hi:[1,0,1]
	v_pk_fma_f32 v[16:17], v[16:17], v[198:199], v[182:183] op_sel_hi:[1,0,1]
	v_pk_fma_f32 v[18:19], v[18:19], v[198:199], v[184:185] op_sel_hi:[1,0,1]
	v_exp_f32_e32 v28, v28
	v_exp_f32_e32 v29, v29
	v_exp_f32_e32 v30, v30
	v_exp_f32_e32 v31, v31
	v_exp_f32_e32 v24, v24
	v_exp_f32_e32 v25, v25
	v_exp_f32_e32 v26, v26
	v_exp_f32_e32 v27, v27
	v_exp_f32_e32 v20, v20
	v_exp_f32_e32 v21, v21
	v_exp_f32_e32 v22, v22
	v_exp_f32_e32 v23, v23
	v_exp_f32_e32 v16, v16
	v_exp_f32_e32 v17, v17
	v_exp_f32_e32 v18, v18
	v_exp_f32_e32 v19, v19
	s_nop 0
	v_pk_add_f32 v[28:29], v[28:29], v[216:217]
	v_pk_add_f32 v[30:31], v[30:31], v[216:217]
	v_pk_add_f32 v[24:25], v[24:25], v[216:217]
	v_pk_add_f32 v[26:27], v[26:27], v[216:217]
	v_pk_add_f32 v[20:21], v[20:21], v[216:217]
	v_pk_add_f32 v[22:23], v[22:23], v[216:217]
	v_pk_add_f32 v[16:17], v[16:17], v[216:217]
	v_pk_add_f32 v[18:19], v[18:19], v[216:217]
	v_rcp_f32_e32 v28, v28
	v_rcp_f32_e32 v29, v29
	v_rcp_f32_e32 v30, v30
	v_rcp_f32_e32 v31, v31
	v_rcp_f32_e32 v24, v24
	v_rcp_f32_e32 v25, v25
	v_rcp_f32_e32 v26, v26
	v_rcp_f32_e32 v27, v27
	v_rcp_f32_e32 v20, v20
	v_rcp_f32_e32 v21, v21
	v_rcp_f32_e32 v22, v22
	v_rcp_f32_e32 v23, v23
	v_rcp_f32_e32 v16, v16
	v_rcp_f32_e32 v17, v17
	v_rcp_f32_e32 v18, v18
	v_rcp_f32_e32 v19, v19
	s_nop 0
	v_cvt_pk_bf16_f32 v28, v28, v29
	v_cvt_pk_bf16_f32 v29, v30, v31
	v_cvt_pk_bf16_f32 v30, v24, v25
	v_cvt_pk_bf16_f32 v31, v26, v27
	global_store_dwordx4 v212, v[28:31], s[10:11]
	v_cvt_pk_bf16_f32 v20, v20, v21
	v_cvt_pk_bf16_f32 v21, v22, v23
	v_cvt_pk_bf16_f32 v22, v16, v17
	v_cvt_pk_bf16_f32 v23, v18, v19
	global_store_dwordx4 v212, v[20:23], s[10:11] offset:256
	v_pk_fma_f32 v[12:13], v[12:13], v[200:201], v[170:171] op_sel_hi:[1,0,1]
	v_pk_fma_f32 v[14:15], v[14:15], v[200:201], v[172:173] op_sel_hi:[1,0,1]
	v_pk_fma_f32 v[8:9], v[8:9], v[200:201], v[174:175] op_sel_hi:[1,0,1]
	v_pk_fma_f32 v[10:11], v[10:11], v[200:201], v[176:177] op_sel_hi:[1,0,1]
	v_pk_fma_f32 v[4:5], v[4:5], v[200:201], v[178:179] op_sel_hi:[1,0,1]
	v_pk_fma_f32 v[6:7], v[6:7], v[200:201], v[180:181] op_sel_hi:[1,0,1]
	v_pk_fma_f32 v[0:1], v[0:1], v[200:201], v[182:183] op_sel_hi:[1,0,1]
	v_pk_fma_f32 v[2:3], v[2:3], v[200:201], v[184:185] op_sel_hi:[1,0,1]
	v_exp_f32_e32 v12, v12
	v_exp_f32_e32 v13, v13
	v_exp_f32_e32 v14, v14
	v_exp_f32_e32 v15, v15
	v_exp_f32_e32 v8, v8
	v_exp_f32_e32 v9, v9
	v_exp_f32_e32 v10, v10
	v_exp_f32_e32 v11, v11
	v_exp_f32_e32 v4, v4
	v_exp_f32_e32 v5, v5
	v_exp_f32_e32 v6, v6
	v_exp_f32_e32 v7, v7
	v_exp_f32_e32 v0, v0
	v_exp_f32_e32 v1, v1
	v_exp_f32_e32 v2, v2
	v_exp_f32_e32 v3, v3
	s_nop 0
	v_pk_add_f32 v[12:13], v[12:13], v[216:217]
	v_pk_add_f32 v[14:15], v[14:15], v[216:217]
	v_pk_add_f32 v[8:9], v[8:9], v[216:217]
	v_pk_add_f32 v[10:11], v[10:11], v[216:217]
	v_pk_add_f32 v[4:5], v[4:5], v[216:217]
	v_pk_add_f32 v[6:7], v[6:7], v[216:217]
	v_pk_add_f32 v[0:1], v[0:1], v[216:217]
	v_pk_add_f32 v[2:3], v[2:3], v[216:217]
	v_rcp_f32_e32 v12, v12
	v_rcp_f32_e32 v13, v13
	v_rcp_f32_e32 v14, v14
	v_rcp_f32_e32 v15, v15
	v_rcp_f32_e32 v8, v8
	v_rcp_f32_e32 v9, v9
	v_rcp_f32_e32 v10, v10
	v_rcp_f32_e32 v11, v11
	v_rcp_f32_e32 v4, v4
	v_rcp_f32_e32 v5, v5
	v_rcp_f32_e32 v6, v6
	v_rcp_f32_e32 v7, v7
	v_rcp_f32_e32 v0, v0
	v_rcp_f32_e32 v1, v1
	v_rcp_f32_e32 v2, v2
	v_rcp_f32_e32 v3, v3
	s_nop 0
	v_cvt_pk_bf16_f32 v12, v12, v13
	v_cvt_pk_bf16_f32 v13, v14, v15
	v_cvt_pk_bf16_f32 v14, v8, v9
	v_cvt_pk_bf16_f32 v15, v10, v11
	global_store_dwordx4 v213, v[12:15], s[10:11]
	v_cvt_pk_bf16_f32 v4, v4, v5
	v_cvt_pk_bf16_f32 v5, v6, v7
	v_cvt_pk_bf16_f32 v6, v0, v1
	v_cvt_pk_bf16_f32 v7, v2, v3
	global_store_dwordx4 v213, v[4:7], s[10:11] offset:256
	s_andn2_b64 vcc, exec, s[6:7]
	s_mov_b64 s[6:7], -1
	s_cbranch_vccnz .LBB0_1087
	s_and_b64 vcc, exec, s[0:1]
	s_cbranch_vccnz .LBB0_1086
	s_barrier
	s_branch .LBB0_1086
